# out-projection epilogue: residual loads batched and the bf16 stores widened with v_permlane16_swap (two 8-byte stores 32 B apart become one 16-byte store per lane)
# speedup vs baseline: 1.0039x; 1.0039x over previous
.LBB0_430:
	v_lshl_add_u32 v151, s22, 8, v144
	v_lshl_or_b32 v152, s24, 8, v146
	v_lshl_add_u32 v153, v151, 10, v152
	v_lshlrev_b32_e32 v154, 2, v153
	s_add_u32 s74, s72, 0x0
	s_addc_u32 s75, s73, 0
	global_load_dwordx4 v[188:191], v154, s[74:75]
	global_load_dwordx4 v[192:195], v154, s[74:75] offset:64
	global_load_dwordx4 v[196:199], v154, s[74:75] offset:512
	global_load_dwordx4 v[200:203], v154, s[74:75] offset:576
	s_add_u32 s74, s72, 0x10000
	s_addc_u32 s75, s73, 0
	global_load_dwordx4 v[204:207], v154, s[74:75]
	global_load_dwordx4 v[208:211], v154, s[74:75] offset:64
	global_load_dwordx4 v[212:215], v154, s[74:75] offset:512
	global_load_dwordx4 v[216:219], v154, s[74:75] offset:576
	s_add_u32 s74, s72, 0x20000
	s_addc_u32 s75, s73, 0
	global_load_dwordx4 v[220:223], v154, s[74:75]
	global_load_dwordx4 v[224:227], v154, s[74:75] offset:64
	global_load_dwordx4 v[228:231], v154, s[74:75] offset:512
	global_load_dwordx4 v[232:235], v154, s[74:75] offset:576
	s_add_u32 s74, s72, 0x30000
	s_addc_u32 s75, s73, 0
	global_load_dwordx4 v[236:239], v154, s[74:75]
	global_load_dwordx4 v[240:243], v154, s[74:75] offset:64
	global_load_dwordx4 v[244:247], v154, s[74:75] offset:512
	global_load_dwordx4 v[248:251], v154, s[74:75] offset:576
	v_lshlrev_b32_e32 v155, 1, v153
	v_and_b32_e32 v176, 16, v150
	v_mul_u32_u24_e32 v176, 3, v176
	v_lshrrev_b32_e32 v176, 1, v176
	v_add_u32_e32 v176, v176, v155
	v_lshlrev_b32_e32 v156, 3, v151
	v_xor_b32_e32 v157, 16, v150
	v_lshlrev_b32_e32 v157, 2, v157
	v_xor_b32_e32 v158, 32, v150
	v_lshlrev_b32_e32 v158, 2, v158
	s_waitcnt vmcnt(12)
	v_pk_fma_f32 v[188:189], v[188:189], s[12:13], v[124:125] op_sel_hi:[1,0,1]
	v_pk_fma_f32 v[190:191], v[190:191], s[12:13], v[126:127] op_sel_hi:[1,0,1]
	v_pk_fma_f32 v[192:193], v[192:193], s[12:13], v[120:121] op_sel_hi:[1,0,1]
	v_pk_fma_f32 v[194:195], v[194:195], s[12:13], v[122:123] op_sel_hi:[1,0,1]
	v_pk_fma_f32 v[196:197], v[196:197], s[12:13], v[116:117] op_sel_hi:[1,0,1]
	v_pk_fma_f32 v[198:199], v[198:199], s[12:13], v[118:119] op_sel_hi:[1,0,1]
	v_pk_fma_f32 v[200:201], v[200:201], s[12:13], v[112:113] op_sel_hi:[1,0,1]
	v_pk_fma_f32 v[202:203], v[202:203], s[12:13], v[114:115] op_sel_hi:[1,0,1]
	s_add_u32 s82, s88, 0x0
	s_addc_u32 s83, s89, 0
	v_cvt_pk_bf16_f32 v160, v188, v189
	v_cvt_pk_bf16_f32 v161, v190, v191
	v_cvt_pk_bf16_f32 v162, v192, v193
	v_cvt_pk_bf16_f32 v163, v194, v195
	v_cvt_pk_bf16_f32 v164, v196, v197
	v_cvt_pk_bf16_f32 v165, v198, v199
	v_cvt_pk_bf16_f32 v166, v200, v201
	v_cvt_pk_bf16_f32 v167, v202, v203
	s_nop 1
	v_permlane16_swap_b32 v160, v162
	v_permlane16_swap_b32 v161, v163
	v_permlane16_swap_b32 v164, v166
	v_permlane16_swap_b32 v165, v167
	global_store_dwordx4 v176, v[160:163], s[82:83]
	global_store_dwordx4 v176, v[164:167], s[82:83] offset:256
	v_add_f32_e32 v168, v188, v189
	v_add_f32_e32 v169, v190, v191
	v_mul_f32_e32 v172, v189, v189
	v_mul_f32_e32 v173, v191, v191
	v_add_f32_e32 v168, v168, v169
	v_fma_f32 v172, v188, v188, v172
	v_fma_f32 v173, v190, v190, v173
	v_add_f32_e32 v170, 0, v168
	v_add_f32_e32 v171, v172, v173
	v_add_f32_e32 v168, v192, v193
	v_add_f32_e32 v169, v194, v195
	v_mul_f32_e32 v172, v193, v193
	v_mul_f32_e32 v173, v195, v195
	v_add_f32_e32 v168, v168, v169
	v_fma_f32 v172, v192, v192, v172
	v_fma_f32 v173, v194, v194, v173
	v_add_f32_e32 v170, v170, v168
	v_add_f32_e32 v172, v172, v173
	v_add_f32_e32 v171, v171, v172
	v_add_f32_e32 v168, v196, v197
	v_add_f32_e32 v169, v198, v199
	v_mul_f32_e32 v172, v197, v197
	v_mul_f32_e32 v173, v199, v199
	v_add_f32_e32 v168, v168, v169
	v_fma_f32 v172, v196, v196, v172
	v_fma_f32 v173, v198, v198, v173
	v_add_f32_e32 v170, v170, v168
	v_add_f32_e32 v172, v172, v173
	v_add_f32_e32 v171, v171, v172
	v_add_f32_e32 v168, v200, v201
	v_add_f32_e32 v169, v202, v203
	v_mul_f32_e32 v172, v201, v201
	v_mul_f32_e32 v173, v203, v203
	v_add_f32_e32 v168, v168, v169
	v_fma_f32 v172, v200, v200, v172
	v_fma_f32 v173, v202, v202, v173
	v_add_f32_e32 v170, v170, v168
	v_add_f32_e32 v172, v172, v173
	v_add_f32_e32 v171, v171, v172
	s_add_u32 s74, s72, 0x80000
	s_addc_u32 s75, s73, 0
	global_load_dwordx4 v[188:191], v154, s[74:75]
	global_load_dwordx4 v[192:195], v154, s[74:75] offset:64
	global_load_dwordx4 v[196:199], v154, s[74:75] offset:512
	global_load_dwordx4 v[200:203], v154, s[74:75] offset:576
	ds_bpermute_b32 v174, v157, v170
	ds_bpermute_b32 v175, v157, v171
	s_waitcnt lgkmcnt(0)
	v_add_f32_e32 v170, v170, v174
	v_add_f32_e32 v171, v171, v175
	ds_bpermute_b32 v174, v158, v170
	ds_bpermute_b32 v175, v158, v171
	s_waitcnt lgkmcnt(0)
	v_add_f32_e32 v170, v170, v174
	v_add_f32_e32 v171, v171, v175
	s_and_saveexec_b64 s[22:23], s[2:3]
	global_atomic_add_f32 v156, v170, s[6:7]
	global_atomic_add_f32 v156, v171, s[6:7] offset:4
	s_or_b64 exec, exec, s[22:23]
	s_waitcnt vmcnt(16)
	v_pk_fma_f32 v[204:205], v[204:205], s[12:13], v[108:109] op_sel_hi:[1,0,1]
	v_pk_fma_f32 v[206:207], v[206:207], s[12:13], v[110:111] op_sel_hi:[1,0,1]
	v_pk_fma_f32 v[208:209], v[208:209], s[12:13], v[104:105] op_sel_hi:[1,0,1]
	v_pk_fma_f32 v[210:211], v[210:211], s[12:13], v[106:107] op_sel_hi:[1,0,1]
	v_pk_fma_f32 v[212:213], v[212:213], s[12:13], v[100:101] op_sel_hi:[1,0,1]
	v_pk_fma_f32 v[214:215], v[214:215], s[12:13], v[102:103] op_sel_hi:[1,0,1]
	v_pk_fma_f32 v[216:217], v[216:217], s[12:13], v[96:97] op_sel_hi:[1,0,1]
	v_pk_fma_f32 v[218:219], v[218:219], s[12:13], v[98:99] op_sel_hi:[1,0,1]
	s_add_u32 s82, s88, 0x8000
	s_addc_u32 s83, s89, 0
	v_cvt_pk_bf16_f32 v160, v204, v205
	v_cvt_pk_bf16_f32 v161, v206, v207
	v_cvt_pk_bf16_f32 v162, v208, v209
	v_cvt_pk_bf16_f32 v163, v210, v211
	v_cvt_pk_bf16_f32 v164, v212, v213
	v_cvt_pk_bf16_f32 v165, v214, v215
	v_cvt_pk_bf16_f32 v166, v216, v217
	v_cvt_pk_bf16_f32 v167, v218, v219
	s_nop 1
	v_permlane16_swap_b32 v160, v162
	v_permlane16_swap_b32 v161, v163
	v_permlane16_swap_b32 v164, v166
	v_permlane16_swap_b32 v165, v167
	global_store_dwordx4 v176, v[160:163], s[82:83]
	global_store_dwordx4 v176, v[164:167], s[82:83] offset:256
	v_add_f32_e32 v168, v204, v205
	v_add_f32_e32 v169, v206, v207
	v_mul_f32_e32 v172, v205, v205
	v_mul_f32_e32 v173, v207, v207
	v_add_f32_e32 v168, v168, v169
	v_fma_f32 v172, v204, v204, v172
	v_fma_f32 v173, v206, v206, v173
	v_add_f32_e32 v170, 0, v168
	v_add_f32_e32 v171, v172, v173
	v_add_f32_e32 v168, v208, v209
	v_add_f32_e32 v169, v210, v211
	v_mul_f32_e32 v172, v209, v209
	v_mul_f32_e32 v173, v211, v211
	v_add_f32_e32 v168, v168, v169
	v_fma_f32 v172, v208, v208, v172
	v_fma_f32 v173, v210, v210, v173
	v_add_f32_e32 v170, v170, v168
	v_add_f32_e32 v172, v172, v173
	v_add_f32_e32 v171, v171, v172
	v_add_f32_e32 v168, v212, v213
	v_add_f32_e32 v169, v214, v215
	v_mul_f32_e32 v172, v213, v213
	v_mul_f32_e32 v173, v215, v215
	v_add_f32_e32 v168, v168, v169
	v_fma_f32 v172, v212, v212, v172
	v_fma_f32 v173, v214, v214, v173
	v_add_f32_e32 v170, v170, v168
	v_add_f32_e32 v172, v172, v173
	v_add_f32_e32 v171, v171, v172
	v_add_f32_e32 v168, v216, v217
	v_add_f32_e32 v169, v218, v219
	v_mul_f32_e32 v172, v217, v217
	v_mul_f32_e32 v173, v219, v219
	v_add_f32_e32 v168, v168, v169
	v_fma_f32 v172, v216, v216, v172
	v_fma_f32 v173, v218, v218, v173
	v_add_f32_e32 v170, v170, v168
	v_add_f32_e32 v172, v172, v173
	v_add_f32_e32 v171, v171, v172
	s_add_u32 s74, s72, 0x90000
	s_addc_u32 s75, s73, 0
	global_load_dwordx4 v[204:207], v154, s[74:75]
	global_load_dwordx4 v[208:211], v154, s[74:75] offset:64
	global_load_dwordx4 v[212:215], v154, s[74:75] offset:512
	global_load_dwordx4 v[216:219], v154, s[74:75] offset:576
	ds_bpermute_b32 v174, v157, v170
	ds_bpermute_b32 v175, v157, v171
	s_waitcnt lgkmcnt(0)
	v_add_f32_e32 v170, v170, v174
	v_add_f32_e32 v171, v171, v175
	ds_bpermute_b32 v174, v158, v170
	ds_bpermute_b32 v175, v158, v171
	s_waitcnt lgkmcnt(0)
	v_add_f32_e32 v170, v170, v174
	v_add_f32_e32 v171, v171, v175
	s_and_saveexec_b64 s[22:23], s[2:3]
	global_atomic_add_f32 v156, v170, s[6:7] offset:128
	global_atomic_add_f32 v156, v171, s[6:7] offset:132
	s_or_b64 exec, exec, s[22:23]
	s_waitcnt vmcnt(20)
	v_pk_fma_f32 v[220:221], v[220:221], s[12:13], v[92:93] op_sel_hi:[1,0,1]
	v_pk_fma_f32 v[222:223], v[222:223], s[12:13], v[94:95] op_sel_hi:[1,0,1]
	v_pk_fma_f32 v[224:225], v[224:225], s[12:13], v[88:89] op_sel_hi:[1,0,1]
	v_pk_fma_f32 v[226:227], v[226:227], s[12:13], v[90:91] op_sel_hi:[1,0,1]
	v_pk_fma_f32 v[228:229], v[228:229], s[12:13], v[84:85] op_sel_hi:[1,0,1]
	v_pk_fma_f32 v[230:231], v[230:231], s[12:13], v[86:87] op_sel_hi:[1,0,1]
	v_pk_fma_f32 v[232:233], v[232:233], s[12:13], v[80:81] op_sel_hi:[1,0,1]
	v_pk_fma_f32 v[234:235], v[234:235], s[12:13], v[82:83] op_sel_hi:[1,0,1]
	s_add_u32 s82, s88, 0x10000
	s_addc_u32 s83, s89, 0
	v_cvt_pk_bf16_f32 v160, v220, v221
	v_cvt_pk_bf16_f32 v161, v222, v223
	v_cvt_pk_bf16_f32 v162, v224, v225
	v_cvt_pk_bf16_f32 v163, v226, v227
	v_cvt_pk_bf16_f32 v164, v228, v229
	v_cvt_pk_bf16_f32 v165, v230, v231
	v_cvt_pk_bf16_f32 v166, v232, v233
	v_cvt_pk_bf16_f32 v167, v234, v235
	s_nop 1
	v_permlane16_swap_b32 v160, v162
	v_permlane16_swap_b32 v161, v163
	v_permlane16_swap_b32 v164, v166
	v_permlane16_swap_b32 v165, v167
	global_store_dwordx4 v176, v[160:163], s[82:83]
	global_store_dwordx4 v176, v[164:167], s[82:83] offset:256
	v_add_f32_e32 v168, v220, v221
	v_add_f32_e32 v169, v222, v223
	v_mul_f32_e32 v172, v221, v221
	v_mul_f32_e32 v173, v223, v223
	v_add_f32_e32 v168, v168, v169
	v_fma_f32 v172, v220, v220, v172
	v_fma_f32 v173, v222, v222, v173
	v_add_f32_e32 v170, 0, v168
	v_add_f32_e32 v171, v172, v173
	v_add_f32_e32 v168, v224, v225
	v_add_f32_e32 v169, v226, v227
	v_mul_f32_e32 v172, v225, v225
	v_mul_f32_e32 v173, v227, v227
	v_add_f32_e32 v168, v168, v169
	v_fma_f32 v172, v224, v224, v172
	v_fma_f32 v173, v226, v226, v173
	v_add_f32_e32 v170, v170, v168
	v_add_f32_e32 v172, v172, v173
	v_add_f32_e32 v171, v171, v172
	v_add_f32_e32 v168, v228, v229
	v_add_f32_e32 v169, v230, v231
	v_mul_f32_e32 v172, v229, v229
	v_mul_f32_e32 v173, v231, v231
	v_add_f32_e32 v168, v168, v169
	v_fma_f32 v172, v228, v228, v172
	v_fma_f32 v173, v230, v230, v173
	v_add_f32_e32 v170, v170, v168
	v_add_f32_e32 v172, v172, v173
	v_add_f32_e32 v171, v171, v172
	v_add_f32_e32 v168, v232, v233
	v_add_f32_e32 v169, v234, v235
	v_mul_f32_e32 v172, v233, v233
	v_mul_f32_e32 v173, v235, v235
	v_add_f32_e32 v168, v168, v169
	v_fma_f32 v172, v232, v232, v172
	v_fma_f32 v173, v234, v234, v173
	v_add_f32_e32 v170, v170, v168
	v_add_f32_e32 v172, v172, v173
	v_add_f32_e32 v171, v171, v172
	s_add_u32 s74, s72, 0xa0000
	s_addc_u32 s75, s73, 0
	global_load_dwordx4 v[220:223], v154, s[74:75]
	global_load_dwordx4 v[224:227], v154, s[74:75] offset:64
	global_load_dwordx4 v[228:231], v154, s[74:75] offset:512
	global_load_dwordx4 v[232:235], v154, s[74:75] offset:576
	ds_bpermute_b32 v174, v157, v170
	ds_bpermute_b32 v175, v157, v171
	s_waitcnt lgkmcnt(0)
	v_add_f32_e32 v170, v170, v174
	v_add_f32_e32 v171, v171, v175
	ds_bpermute_b32 v174, v158, v170
	ds_bpermute_b32 v175, v158, v171
	s_waitcnt lgkmcnt(0)
	v_add_f32_e32 v170, v170, v174
	v_add_f32_e32 v171, v171, v175
	s_and_saveexec_b64 s[22:23], s[2:3]
	global_atomic_add_f32 v156, v170, s[6:7] offset:256
	global_atomic_add_f32 v156, v171, s[6:7] offset:260
	s_or_b64 exec, exec, s[22:23]
	s_waitcnt vmcnt(24)
	v_pk_fma_f32 v[236:237], v[236:237], s[12:13], v[76:77] op_sel_hi:[1,0,1]
	v_pk_fma_f32 v[238:239], v[238:239], s[12:13], v[78:79] op_sel_hi:[1,0,1]
	v_pk_fma_f32 v[240:241], v[240:241], s[12:13], v[72:73] op_sel_hi:[1,0,1]
	v_pk_fma_f32 v[242:243], v[242:243], s[12:13], v[74:75] op_sel_hi:[1,0,1]
	v_pk_fma_f32 v[244:245], v[244:245], s[12:13], v[68:69] op_sel_hi:[1,0,1]
	v_pk_fma_f32 v[246:247], v[246:247], s[12:13], v[70:71] op_sel_hi:[1,0,1]
	v_pk_fma_f32 v[248:249], v[248:249], s[12:13], v[64:65] op_sel_hi:[1,0,1]
	v_pk_fma_f32 v[250:251], v[250:251], s[12:13], v[66:67] op_sel_hi:[1,0,1]
	s_add_u32 s82, s88, 0x18000
	s_addc_u32 s83, s89, 0
	v_cvt_pk_bf16_f32 v160, v236, v237
	v_cvt_pk_bf16_f32 v161, v238, v239
	v_cvt_pk_bf16_f32 v162, v240, v241
	v_cvt_pk_bf16_f32 v163, v242, v243
	v_cvt_pk_bf16_f32 v164, v244, v245
	v_cvt_pk_bf16_f32 v165, v246, v247
	v_cvt_pk_bf16_f32 v166, v248, v249
	v_cvt_pk_bf16_f32 v167, v250, v251
	s_nop 1
	v_permlane16_swap_b32 v160, v162
	v_permlane16_swap_b32 v161, v163
	v_permlane16_swap_b32 v164, v166
	v_permlane16_swap_b32 v165, v167
	global_store_dwordx4 v176, v[160:163], s[82:83]
	global_store_dwordx4 v176, v[164:167], s[82:83] offset:256
	v_add_f32_e32 v168, v236, v237
	v_add_f32_e32 v169, v238, v239
	v_mul_f32_e32 v172, v237, v237
	v_mul_f32_e32 v173, v239, v239
	v_add_f32_e32 v168, v168, v169
	v_fma_f32 v172, v236, v236, v172
	v_fma_f32 v173, v238, v238, v173
	v_add_f32_e32 v170, 0, v168
	v_add_f32_e32 v171, v172, v173
	v_add_f32_e32 v168, v240, v241
	v_add_f32_e32 v169, v242, v243
	v_mul_f32_e32 v172, v241, v241
	v_mul_f32_e32 v173, v243, v243
	v_add_f32_e32 v168, v168, v169
	v_fma_f32 v172, v240, v240, v172
	v_fma_f32 v173, v242, v242, v173
	v_add_f32_e32 v170, v170, v168
	v_add_f32_e32 v172, v172, v173
	v_add_f32_e32 v171, v171, v172
	v_add_f32_e32 v168, v244, v245
	v_add_f32_e32 v169, v246, v247
	v_mul_f32_e32 v172, v245, v245
	v_mul_f32_e32 v173, v247, v247
	v_add_f32_e32 v168, v168, v169
	v_fma_f32 v172, v244, v244, v172
	v_fma_f32 v173, v246, v246, v173
	v_add_f32_e32 v170, v170, v168
	v_add_f32_e32 v172, v172, v173
	v_add_f32_e32 v171, v171, v172
	v_add_f32_e32 v168, v248, v249
	v_add_f32_e32 v169, v250, v251
	v_mul_f32_e32 v172, v249, v249
	v_mul_f32_e32 v173, v251, v251
	v_add_f32_e32 v168, v168, v169
	v_fma_f32 v172, v248, v248, v172
	v_fma_f32 v173, v250, v250, v173
	v_add_f32_e32 v170, v170, v168
	v_add_f32_e32 v172, v172, v173
	v_add_f32_e32 v171, v171, v172
	s_add_u32 s74, s72, 0xb0000
	s_addc_u32 s75, s73, 0
	global_load_dwordx4 v[236:239], v154, s[74:75]
	global_load_dwordx4 v[240:243], v154, s[74:75] offset:64
	global_load_dwordx4 v[244:247], v154, s[74:75] offset:512
	global_load_dwordx4 v[248:251], v154, s[74:75] offset:576
	ds_bpermute_b32 v174, v157, v170
	ds_bpermute_b32 v175, v157, v171
	s_waitcnt lgkmcnt(0)
	v_add_f32_e32 v170, v170, v174
	v_add_f32_e32 v171, v171, v175
	ds_bpermute_b32 v174, v158, v170
	ds_bpermute_b32 v175, v158, v171
	s_waitcnt lgkmcnt(0)
	v_add_f32_e32 v170, v170, v174
	v_add_f32_e32 v171, v171, v175
	s_and_saveexec_b64 s[22:23], s[2:3]
	global_atomic_add_f32 v156, v170, s[6:7] offset:384
	global_atomic_add_f32 v156, v171, s[6:7] offset:388
	s_or_b64 exec, exec, s[22:23]
	s_waitcnt vmcnt(26)
	v_pk_fma_f32 v[188:189], v[188:189], s[12:13], v[60:61] op_sel_hi:[1,0,1]
	v_pk_fma_f32 v[190:191], v[190:191], s[12:13], v[62:63] op_sel_hi:[1,0,1]
	v_pk_fma_f32 v[192:193], v[192:193], s[12:13], v[56:57] op_sel_hi:[1,0,1]
	v_pk_fma_f32 v[194:195], v[194:195], s[12:13], v[58:59] op_sel_hi:[1,0,1]
	v_pk_fma_f32 v[196:197], v[196:197], s[12:13], v[52:53] op_sel_hi:[1,0,1]
	v_pk_fma_f32 v[198:199], v[198:199], s[12:13], v[54:55] op_sel_hi:[1,0,1]
	v_pk_fma_f32 v[200:201], v[200:201], s[12:13], v[48:49] op_sel_hi:[1,0,1]
	v_pk_fma_f32 v[202:203], v[202:203], s[12:13], v[50:51] op_sel_hi:[1,0,1]
	s_add_u32 s82, s88, 0x40000
	s_addc_u32 s83, s89, 0
	v_cvt_pk_bf16_f32 v160, v188, v189
	v_cvt_pk_bf16_f32 v161, v190, v191
	v_cvt_pk_bf16_f32 v162, v192, v193
	v_cvt_pk_bf16_f32 v163, v194, v195
	v_cvt_pk_bf16_f32 v164, v196, v197
	v_cvt_pk_bf16_f32 v165, v198, v199
	v_cvt_pk_bf16_f32 v166, v200, v201
	v_cvt_pk_bf16_f32 v167, v202, v203
	s_nop 1
	v_permlane16_swap_b32 v160, v162
	v_permlane16_swap_b32 v161, v163
	v_permlane16_swap_b32 v164, v166
	v_permlane16_swap_b32 v165, v167
	global_store_dwordx4 v176, v[160:163], s[82:83]
	global_store_dwordx4 v176, v[164:167], s[82:83] offset:256
	v_add_f32_e32 v168, v188, v189
	v_add_f32_e32 v169, v190, v191
	v_mul_f32_e32 v172, v189, v189
	v_mul_f32_e32 v173, v191, v191
	v_add_f32_e32 v168, v168, v169
	v_fma_f32 v172, v188, v188, v172
	v_fma_f32 v173, v190, v190, v173
	v_add_f32_e32 v170, 0, v168
	v_add_f32_e32 v171, v172, v173
	v_add_f32_e32 v168, v192, v193
	v_add_f32_e32 v169, v194, v195
	v_mul_f32_e32 v172, v193, v193
	v_mul_f32_e32 v173, v195, v195
	v_add_f32_e32 v168, v168, v169
	v_fma_f32 v172, v192, v192, v172
	v_fma_f32 v173, v194, v194, v173
	v_add_f32_e32 v170, v170, v168
	v_add_f32_e32 v172, v172, v173
	v_add_f32_e32 v171, v171, v172
	v_add_f32_e32 v168, v196, v197
	v_add_f32_e32 v169, v198, v199
	v_mul_f32_e32 v172, v197, v197
	v_mul_f32_e32 v173, v199, v199
	v_add_f32_e32 v168, v168, v169
	v_fma_f32 v172, v196, v196, v172
	v_fma_f32 v173, v198, v198, v173
	v_add_f32_e32 v170, v170, v168
	v_add_f32_e32 v172, v172, v173
	v_add_f32_e32 v171, v171, v172
	v_add_f32_e32 v168, v200, v201
	v_add_f32_e32 v169, v202, v203
	v_mul_f32_e32 v172, v201, v201
	v_mul_f32_e32 v173, v203, v203
	v_add_f32_e32 v168, v168, v169
	v_fma_f32 v172, v200, v200, v172
	v_fma_f32 v173, v202, v202, v173
	v_add_f32_e32 v170, v170, v168
	v_add_f32_e32 v172, v172, v173
	v_add_f32_e32 v171, v171, v172
	ds_bpermute_b32 v174, v157, v170
	ds_bpermute_b32 v175, v157, v171
	s_waitcnt lgkmcnt(0)
	v_add_f32_e32 v170, v170, v174
	v_add_f32_e32 v171, v171, v175
	ds_bpermute_b32 v174, v158, v170
	ds_bpermute_b32 v175, v158, v171
	s_waitcnt lgkmcnt(0)
	v_add_f32_e32 v170, v170, v174
	v_add_f32_e32 v171, v171, v175
	s_and_saveexec_b64 s[22:23], s[2:3]
	global_atomic_add_f32 v156, v170, s[6:7] offset:1024
	global_atomic_add_f32 v156, v171, s[6:7] offset:1028
	s_or_b64 exec, exec, s[22:23]
	s_waitcnt vmcnt(22)
	v_pk_fma_f32 v[204:205], v[204:205], s[12:13], v[44:45] op_sel_hi:[1,0,1]
	v_pk_fma_f32 v[206:207], v[206:207], s[12:13], v[46:47] op_sel_hi:[1,0,1]
	v_pk_fma_f32 v[208:209], v[208:209], s[12:13], v[40:41] op_sel_hi:[1,0,1]
	v_pk_fma_f32 v[210:211], v[210:211], s[12:13], v[42:43] op_sel_hi:[1,0,1]
	v_pk_fma_f32 v[212:213], v[212:213], s[12:13], v[36:37] op_sel_hi:[1,0,1]
	v_pk_fma_f32 v[214:215], v[214:215], s[12:13], v[38:39] op_sel_hi:[1,0,1]
	v_pk_fma_f32 v[216:217], v[216:217], s[12:13], v[32:33] op_sel_hi:[1,0,1]
	v_pk_fma_f32 v[218:219], v[218:219], s[12:13], v[34:35] op_sel_hi:[1,0,1]
	s_add_u32 s82, s88, 0x48000
	s_addc_u32 s83, s89, 0
	v_cvt_pk_bf16_f32 v160, v204, v205
	v_cvt_pk_bf16_f32 v161, v206, v207
	v_cvt_pk_bf16_f32 v162, v208, v209
	v_cvt_pk_bf16_f32 v163, v210, v211
	v_cvt_pk_bf16_f32 v164, v212, v213
	v_cvt_pk_bf16_f32 v165, v214, v215
	v_cvt_pk_bf16_f32 v166, v216, v217
	v_cvt_pk_bf16_f32 v167, v218, v219
	s_nop 1
	v_permlane16_swap_b32 v160, v162
	v_permlane16_swap_b32 v161, v163
	v_permlane16_swap_b32 v164, v166
	v_permlane16_swap_b32 v165, v167
	global_store_dwordx4 v176, v[160:163], s[82:83]
	global_store_dwordx4 v176, v[164:167], s[82:83] offset:256
	v_add_f32_e32 v168, v204, v205
	v_add_f32_e32 v169, v206, v207
	v_mul_f32_e32 v172, v205, v205
	v_mul_f32_e32 v173, v207, v207
	v_add_f32_e32 v168, v168, v169
	v_fma_f32 v172, v204, v204, v172
	v_fma_f32 v173, v206, v206, v173
	v_add_f32_e32 v170, 0, v168
	v_add_f32_e32 v171, v172, v173
	v_add_f32_e32 v168, v208, v209
	v_add_f32_e32 v169, v210, v211
	v_mul_f32_e32 v172, v209, v209
	v_mul_f32_e32 v173, v211, v211
	v_add_f32_e32 v168, v168, v169
	v_fma_f32 v172, v208, v208, v172
	v_fma_f32 v173, v210, v210, v173
	v_add_f32_e32 v170, v170, v168
	v_add_f32_e32 v172, v172, v173
	v_add_f32_e32 v171, v171, v172
	v_add_f32_e32 v168, v212, v213
	v_add_f32_e32 v169, v214, v215
	v_mul_f32_e32 v172, v213, v213
	v_mul_f32_e32 v173, v215, v215
	v_add_f32_e32 v168, v168, v169
	v_fma_f32 v172, v212, v212, v172
	v_fma_f32 v173, v214, v214, v173
	v_add_f32_e32 v170, v170, v168
	v_add_f32_e32 v172, v172, v173
	v_add_f32_e32 v171, v171, v172
	v_add_f32_e32 v168, v216, v217
	v_add_f32_e32 v169, v218, v219
	v_mul_f32_e32 v172, v217, v217
	v_mul_f32_e32 v173, v219, v219
	v_add_f32_e32 v168, v168, v169
	v_fma_f32 v172, v216, v216, v172
	v_fma_f32 v173, v218, v218, v173
	v_add_f32_e32 v170, v170, v168
	v_add_f32_e32 v172, v172, v173
	v_add_f32_e32 v171, v171, v172
	ds_bpermute_b32 v174, v157, v170
	ds_bpermute_b32 v175, v157, v171
	s_waitcnt lgkmcnt(0)
	v_add_f32_e32 v170, v170, v174
	v_add_f32_e32 v171, v171, v175
	ds_bpermute_b32 v174, v158, v170
	ds_bpermute_b32 v175, v158, v171
	s_waitcnt lgkmcnt(0)
	v_add_f32_e32 v170, v170, v174
	v_add_f32_e32 v171, v171, v175
	s_and_saveexec_b64 s[22:23], s[2:3]
	global_atomic_add_f32 v156, v170, s[6:7] offset:1152
	global_atomic_add_f32 v156, v171, s[6:7] offset:1156
	s_or_b64 exec, exec, s[22:23]
	s_waitcnt vmcnt(18)
	v_pk_fma_f32 v[220:221], v[220:221], s[12:13], v[28:29] op_sel_hi:[1,0,1]
	v_pk_fma_f32 v[222:223], v[222:223], s[12:13], v[30:31] op_sel_hi:[1,0,1]
	v_pk_fma_f32 v[224:225], v[224:225], s[12:13], v[24:25] op_sel_hi:[1,0,1]
	v_pk_fma_f32 v[226:227], v[226:227], s[12:13], v[26:27] op_sel_hi:[1,0,1]
	v_pk_fma_f32 v[228:229], v[228:229], s[12:13], v[20:21] op_sel_hi:[1,0,1]
	v_pk_fma_f32 v[230:231], v[230:231], s[12:13], v[22:23] op_sel_hi:[1,0,1]
	v_pk_fma_f32 v[232:233], v[232:233], s[12:13], v[16:17] op_sel_hi:[1,0,1]
	v_pk_fma_f32 v[234:235], v[234:235], s[12:13], v[18:19] op_sel_hi:[1,0,1]
	s_add_u32 s82, s88, 0x50000
	s_addc_u32 s83, s89, 0
	v_cvt_pk_bf16_f32 v160, v220, v221
	v_cvt_pk_bf16_f32 v161, v222, v223
	v_cvt_pk_bf16_f32 v162, v224, v225
	v_cvt_pk_bf16_f32 v163, v226, v227
	v_cvt_pk_bf16_f32 v164, v228, v229
	v_cvt_pk_bf16_f32 v165, v230, v231
	v_cvt_pk_bf16_f32 v166, v232, v233
	v_cvt_pk_bf16_f32 v167, v234, v235
	s_nop 1
	v_permlane16_swap_b32 v160, v162
	v_permlane16_swap_b32 v161, v163
	v_permlane16_swap_b32 v164, v166
	v_permlane16_swap_b32 v165, v167
	global_store_dwordx4 v176, v[160:163], s[82:83]
	global_store_dwordx4 v176, v[164:167], s[82:83] offset:256
	v_add_f32_e32 v168, v220, v221
	v_add_f32_e32 v169, v222, v223
	v_mul_f32_e32 v172, v221, v221
	v_mul_f32_e32 v173, v223, v223
	v_add_f32_e32 v168, v168, v169
	v_fma_f32 v172, v220, v220, v172
	v_fma_f32 v173, v222, v222, v173
	v_add_f32_e32 v170, 0, v168
	v_add_f32_e32 v171, v172, v173
	v_add_f32_e32 v168, v224, v225
	v_add_f32_e32 v169, v226, v227
	v_mul_f32_e32 v172, v225, v225
	v_mul_f32_e32 v173, v227, v227
	v_add_f32_e32 v168, v168, v169
	v_fma_f32 v172, v224, v224, v172
	v_fma_f32 v173, v226, v226, v173
	v_add_f32_e32 v170, v170, v168
	v_add_f32_e32 v172, v172, v173
	v_add_f32_e32 v171, v171, v172
	v_add_f32_e32 v168, v228, v229
	v_add_f32_e32 v169, v230, v231
	v_mul_f32_e32 v172, v229, v229
	v_mul_f32_e32 v173, v231, v231
	v_add_f32_e32 v168, v168, v169
	v_fma_f32 v172, v228, v228, v172
	v_fma_f32 v173, v230, v230, v173
	v_add_f32_e32 v170, v170, v168
	v_add_f32_e32 v172, v172, v173
	v_add_f32_e32 v171, v171, v172
	v_add_f32_e32 v168, v232, v233
	v_add_f32_e32 v169, v234, v235
	v_mul_f32_e32 v172, v233, v233
	v_mul_f32_e32 v173, v235, v235
	v_add_f32_e32 v168, v168, v169
	v_fma_f32 v172, v232, v232, v172
	v_fma_f32 v173, v234, v234, v173
	v_add_f32_e32 v170, v170, v168
	v_add_f32_e32 v172, v172, v173
	v_add_f32_e32 v171, v171, v172
	ds_bpermute_b32 v174, v157, v170
	ds_bpermute_b32 v175, v157, v171
	s_waitcnt lgkmcnt(0)
	v_add_f32_e32 v170, v170, v174
	v_add_f32_e32 v171, v171, v175
	ds_bpermute_b32 v174, v158, v170
	ds_bpermute_b32 v175, v158, v171
	s_waitcnt lgkmcnt(0)
	v_add_f32_e32 v170, v170, v174
	v_add_f32_e32 v171, v171, v175
	s_and_saveexec_b64 s[22:23], s[2:3]
	global_atomic_add_f32 v156, v170, s[6:7] offset:1280
	global_atomic_add_f32 v156, v171, s[6:7] offset:1284
	s_or_b64 exec, exec, s[22:23]
	s_waitcnt vmcnt(14)
	v_pk_fma_f32 v[236:237], v[236:237], s[12:13], v[12:13] op_sel_hi:[1,0,1]
	v_pk_fma_f32 v[238:239], v[238:239], s[12:13], v[14:15] op_sel_hi:[1,0,1]
	v_pk_fma_f32 v[240:241], v[240:241], s[12:13], v[8:9] op_sel_hi:[1,0,1]
	v_pk_fma_f32 v[242:243], v[242:243], s[12:13], v[10:11] op_sel_hi:[1,0,1]
	v_pk_fma_f32 v[244:245], v[244:245], s[12:13], v[4:5] op_sel_hi:[1,0,1]
	v_pk_fma_f32 v[246:247], v[246:247], s[12:13], v[6:7] op_sel_hi:[1,0,1]
	v_pk_fma_f32 v[248:249], v[248:249], s[12:13], v[0:1] op_sel_hi:[1,0,1]
	v_pk_fma_f32 v[250:251], v[250:251], s[12:13], v[2:3] op_sel_hi:[1,0,1]
	s_add_u32 s82, s88, 0x58000
	s_addc_u32 s83, s89, 0
	v_cvt_pk_bf16_f32 v160, v236, v237
	v_cvt_pk_bf16_f32 v161, v238, v239
	v_cvt_pk_bf16_f32 v162, v240, v241
	v_cvt_pk_bf16_f32 v163, v242, v243
	v_cvt_pk_bf16_f32 v164, v244, v245
	v_cvt_pk_bf16_f32 v165, v246, v247
	v_cvt_pk_bf16_f32 v166, v248, v249
	v_cvt_pk_bf16_f32 v167, v250, v251
	s_nop 1
	v_permlane16_swap_b32 v160, v162
	v_permlane16_swap_b32 v161, v163
	v_permlane16_swap_b32 v164, v166
	v_permlane16_swap_b32 v165, v167
	global_store_dwordx4 v176, v[160:163], s[82:83]
	global_store_dwordx4 v176, v[164:167], s[82:83] offset:256
	v_add_f32_e32 v168, v236, v237
	v_add_f32_e32 v169, v238, v239
	v_mul_f32_e32 v172, v237, v237
	v_mul_f32_e32 v173, v239, v239
	v_add_f32_e32 v168, v168, v169
	v_fma_f32 v172, v236, v236, v172
	v_fma_f32 v173, v238, v238, v173
	v_add_f32_e32 v170, 0, v168
	v_add_f32_e32 v171, v172, v173
	v_add_f32_e32 v168, v240, v241
	v_add_f32_e32 v169, v242, v243
	v_mul_f32_e32 v172, v241, v241
	v_mul_f32_e32 v173, v243, v243
	v_add_f32_e32 v168, v168, v169
	v_fma_f32 v172, v240, v240, v172
	v_fma_f32 v173, v242, v242, v173
	v_add_f32_e32 v170, v170, v168
	v_add_f32_e32 v172, v172, v173
	v_add_f32_e32 v171, v171, v172
	v_add_f32_e32 v168, v244, v245
	v_add_f32_e32 v169, v246, v247
	v_mul_f32_e32 v172, v245, v245
	v_mul_f32_e32 v173, v247, v247
	v_add_f32_e32 v168, v168, v169
	v_fma_f32 v172, v244, v244, v172
	v_fma_f32 v173, v246, v246, v173
	v_add_f32_e32 v170, v170, v168
	v_add_f32_e32 v172, v172, v173
	v_add_f32_e32 v171, v171, v172
	v_add_f32_e32 v168, v248, v249
	v_add_f32_e32 v169, v250, v251
	v_mul_f32_e32 v172, v249, v249
	v_mul_f32_e32 v173, v251, v251
	v_add_f32_e32 v168, v168, v169
	v_fma_f32 v172, v248, v248, v172
	v_fma_f32 v173, v250, v250, v173
	v_add_f32_e32 v170, v170, v168
	v_add_f32_e32 v172, v172, v173
	v_add_f32_e32 v171, v171, v172
	ds_bpermute_b32 v174, v157, v170
	ds_bpermute_b32 v175, v157, v171
	s_waitcnt lgkmcnt(0)
	v_add_f32_e32 v170, v170, v174
	v_add_f32_e32 v171, v171, v175
	ds_bpermute_b32 v174, v158, v170
	ds_bpermute_b32 v175, v158, v171
	s_waitcnt lgkmcnt(0)
	v_add_f32_e32 v170, v170, v174
	v_add_f32_e32 v171, v171, v175
	s_and_saveexec_b64 s[22:23], s[2:3]
	global_atomic_add_f32 v156, v170, s[6:7] offset:1408
	global_atomic_add_f32 v156, v171, s[6:7] offset:1412
	s_or_b64 exec, exec, s[22:23]
	s_mov_b64 s[22:23], -1
